# stagger: helper waves start each chunk about 0.16 us late (s_sleep 6) so their PREP burst does not collide with the compute waves' chunk prologue
# baseline (speedup 1.0000x reference)
.Lmy_f_hl2:
	s_sleep 6
	s_bfe_u32 s100, s62, 0x20006
	s_lshl_b32 s100, s100, 2
	s_add_i32 s101, s100, -16
	s_add_i32 s100, s100, -12
	s_cmp_lg_u32 s65, 0
	s_cbranch_scc1 .Lmy_f_nol2
	v_add_u32_e32 v70, s101, v70
	v_subrev_u32_e32 v71, s101, v71
	v_add_u32_e32 v21, 64, v70
	v_subrev_u32_e32 v26, 64, v71
	v_cndmask_b32_e64 v32, v26, v21, s[4:5]
	v_ashrrev_i32_e32 v33, 31, v32
	v_lshl_add_u64 v[44:45], v[32:33], 0, s[40:41]
	v_mad_u64_u32 v[46:47], s[96:97], v44, s56, v[50:51]
	v_mad_i32_i24 v47, v45, s56, v47
	v_mov_b32_e32 v166, v46
	v_mov_b32_e32 v167, v47
	global_load_dwordx2 v[26:27], v[46:47], off
	v_mov_b32_e32 v30, v20
	v_mov_b32_e32 v31, v20
	v_cmp_lt_i32_e64 s[96:97], 0, v32
	v_mov_b64_e32 v[28:29], v[30:31]
	s_and_saveexec_b64 s[24:25], s[96:97]
	s_cbranch_execz .Lmy_f_k659
	v_add_co_u32_e32 v28, vcc, 0xfffff000, v46
	s_nop 1
	v_addc_co_u32_e32 v29, vcc, -1, v47, vcc
	global_load_dwordx2 v[28:29], v[28:29], off offset:-2048

.Lmy_ck_drE_h:
	s_waitcnt lgkmcnt(0)
	s_bfe_u32 s96, s62, 0x20006
	s_and_b32 s97, s96, 1
	s_mul_i32 s97, s97, 0x2700
	s_mov_b32 s101, 0x1c000
	s_mov_b32 s100, 0x6100
	s_bitcmp0_b32 s65, 0
	s_cselect_b32 s101, 0xe000, s101
	s_cselect_b32 s100, 0x4e00, s100
	s_cmp_gt_u32 s96, 1
	s_cselect_b32 s100, s100, 0
	s_add_i32 s97, s97, s101
	s_add_i32 s97, s97, s100
	s_mov_b32 s96, s97
	v_and_b32_e32 v72, 3, v233
	v_lshrrev_b32_e32 v73, 2, v233
	v_lshlrev_b32_e32 v72, 2, v72
	v_lshl_add_u32 v72, v73, 8, v72
	v_lshl_add_u32 v72, v234, 6, v72
	s_add_i32 s97, s96, 0x1000
	v_add_u32_e32 v78, s97, v72
	v_xor_b32_e32 v79, v224, v234
	v_lshl_add_u32 v79, v79, 4, s96
	ds_read_b128 v[96:99], v79
	ds_read_b128 v[100:103], v79 offset:1024
	ds_read_b128 v[104:107], v79 offset:2048
	ds_read_b128 v[108:111], v79 offset:3072
	ds_read_b32 v80, v78
	ds_read_b32 v81, v78 offset:16
	ds_read_b32 v82, v78 offset:32
	ds_read_b32 v83, v78 offset:48
	ds_read_b32 v84, v78 offset:1024
	ds_read_b32 v85, v78 offset:1040
	ds_read_b32 v86, v78 offset:1056
	ds_read_b32 v87, v78 offset:1072
	ds_read_b32 v88, v78 offset:2048
	ds_read_b32 v89, v78 offset:2064
	ds_read_b32 v90, v78 offset:2080
	ds_read_b32 v91, v78 offset:2096
	ds_read_b32 v92, v78 offset:3072
	ds_read_b32 v93, v78 offset:3088
	ds_read_b32 v94, v78 offset:3104
	ds_read_b32 v95, v78 offset:3120
	v_lshl_add_u32 v74, v224, 2, s96
	ds_write_b32 v74, v235 offset:9728
	v_add_u32_e32 v75, -1, v233
	v_mov_b32_e32 v76, -1
	v_cndmask_b32_e64 v75, v76, v75, s[98:99]
	v_cmp_lt_u32_e64 s[100:101], 7, v233
	v_add_u32_e32 v76, -8, v233
	v_and_b32_e32 v77, 1, v234
	v_cndmask_b32_e64 v75, v75, v76, s[100:101]
	v_lshlrev_b32_e32 v77, 2, v77
	v_sub_u32_e32 v76, v75, v77
	v_lshlrev_b32_e32 v77, 2, v234
	v_sub_u32_e32 v77, v233, v77
	v_add_u32_e32 v77, -1, v77
	s_waitcnt lgkmcnt(15)
	v_mfma_f32_16x16x4_f32 v[244:247], v80, v96, 0
	v_mfma_f32_16x16x4_f32 v[240:243], v81, v97, 0
	s_waitcnt lgkmcnt(14)
	v_mfma_f32_16x16x4_f32 v[244:247], v82, v98, v[244:247]
	s_waitcnt lgkmcnt(13)
	v_mfma_f32_16x16x4_f32 v[240:243], v83, v99, v[240:243]
	s_waitcnt lgkmcnt(12)
	v_mfma_f32_16x16x4_f32 v[244:247], v84, v100, v[244:247]
	s_waitcnt lgkmcnt(11)
	v_mfma_f32_16x16x4_f32 v[240:243], v85, v101, v[240:243]
	s_waitcnt lgkmcnt(10)
	v_mfma_f32_16x16x4_f32 v[244:247], v86, v102, v[244:247]
	s_waitcnt lgkmcnt(9)
	v_mfma_f32_16x16x4_f32 v[240:243], v87, v103, v[240:243]
	s_waitcnt lgkmcnt(8)
	v_mfma_f32_16x16x4_f32 v[244:247], v88, v104, v[244:247]
	s_waitcnt lgkmcnt(7)
	v_mfma_f32_16x16x4_f32 v[240:243], v89, v105, v[240:243]
	s_waitcnt lgkmcnt(6)
	v_mfma_f32_16x16x4_f32 v[244:247], v90, v106, v[244:247]
	s_waitcnt lgkmcnt(5)
	v_mfma_f32_16x16x4_f32 v[240:243], v91, v107, v[240:243]
	s_waitcnt lgkmcnt(4)
	v_mfma_f32_16x16x4_f32 v[244:247], v92, v108, v[244:247]
	s_waitcnt lgkmcnt(3)
	v_mfma_f32_16x16x4_f32 v[240:243], v93, v109, v[240:243]
	s_waitcnt lgkmcnt(2)
	v_mfma_f32_16x16x4_f32 v[244:247], v94, v110, v[244:247]
	s_waitcnt lgkmcnt(1)
	v_mfma_f32_16x16x4_f32 v[240:243], v95, v111, v[240:243]
	s_nop 9
	v_add_f32_e32 v244, v244, v240
	v_add_f32_e32 v245, v245, v241
	v_add_f32_e32 v246, v246, v242
	v_add_f32_e32 v247, v247, v243
	v_cmp_le_i32_e64 s[96:97], 0, v76
	v_cmp_le_i32_e64 s[100:101], 1, v76
	s_nop 0
	v_cndmask_b32_e64 v128, 0, v244, s[96:97]
	v_cndmask_b32_e64 v129, 0, v245, s[100:101]
	v_cmp_le_i32_e64 s[96:97], 2, v76
	v_cmp_le_i32_e64 s[100:101], 3, v76
	s_nop 0
	v_cndmask_b32_e64 v130, 0, v246, s[96:97]
	v_cndmask_b32_e64 v131, 0, v247, s[100:101]
	s_bfe_u32 s96, s62, 0x20006
	s_and_b32 s97, s96, 1
	s_mul_i32 s97, s97, 0x2700
	s_mov_b32 s101, 0x1c000
	s_mov_b32 s100, 0x6100
	s_bitcmp0_b32 s65, 0
	s_cselect_b32 s101, 0xe000, s101
	s_cselect_b32 s100, 0x4e00, s100
	s_cmp_gt_u32 s96, 1
	s_cselect_b32 s100, s100, 0
	s_add_i32 s97, s97, s101
	s_add_i32 s97, s97, s100
	v_xor_b32_e32 v74, v224, v234
	v_lshl_add_u32 v74, v74, 4, s97
	ds_write_b128 v74, v[128:131] offset:8448
	v_lshlrev_b32_e32 v75, 7, v234
	v_lshl_add_u32 v75, v233, 2, v75
	v_add_u32_e32 v75, s97, v75
	v_cmp_le_i32_e64 s[96:97], 0, v77
	v_cmp_le_i32_e64 s[100:101], 1, v77
	s_nop 0
	v_cndmask_b32_e64 v132, 0, v244, s[96:97]
	v_cndmask_b32_e64 v133, 0, v245, s[100:101]
	v_cmp_le_i32_e64 s[96:97], 2, v77
	v_cmp_le_i32_e64 s[100:101], 3, v77
	s_nop 0
	v_cndmask_b32_e64 v134, 0, v246, s[96:97]
	v_cndmask_b32_e64 v135, 0, v247, s[100:101]
	s_mov_b64 exec, 0x00ff00ff
	ds_write_b32 v75, v132 offset:9472
	ds_write_b32 v75, v133 offset:9504
	ds_write_b32 v75, v134 offset:9536
	ds_write_b32 v75, v135 offset:9568
	s_mov_b64 exec, -1
	s_setprio 0
	s_branch .LBB0_655
	s_nop 0
	s_nop 0
	s_nop 0
	s_nop 0
	s_nop 0
	s_nop 0
	s_nop 0
	s_nop 0
	s_nop 0
	s_nop 0
	s_nop 0
	s_nop 0
	s_nop 0
	s_nop 0
	s_nop 0
	s_nop 0
	s_nop 0
	s_nop 0
	s_nop 0
	s_nop 0
	s_nop 0
	s_nop 0
	s_nop 0
	s_nop 0
	s_nop 0
	s_nop 0
	s_nop 0
	s_nop 0
	s_nop 0
	s_nop 0
	s_nop 0
	s_nop 0
	s_nop 0
	s_nop 0
	s_nop 0
	s_nop 0
	s_nop 0
	s_nop 0
	s_nop 0
	s_nop 0
	s_nop 0
